# rwkv_wy<true> final products: 16 chunk-state loads issued from the previous stage's tail and waited before the next task's staging loads go out (which now stay in flight), row operands read once, colu
# speedup vs baseline: 1.2109x; 1.0079x over previous
.LBB0_1034:
	s_or_b64 exec, exec, s[0:1]
	s_ashr_i32 s4, s72, 3
	v_readlane_b32 s6, v255, 20
	s_ashr_i32 s0, s4, s6
	s_and_b32 s1, s4, s62
	s_sub_i32 s5, s62, s1
	v_mov_b32_e32 v81, s1
	s_lshl_b32 s0, s0, 4
	s_lshl_b32 s1, s74, 1
	v_mov_b32_e32 v80, s5
	s_or_b32 s0, s0, s1
	v_cndmask_b32_e64 v80, v80, v81, s[36:37]
	v_add_u32_e32 v0, s0, v0
	v_lshl_add_u32 v80, v0, s6, v80
	v_ashrrev_i32_e32 v81, 31, v80
	v_readlane_b32 s0, v253, 7
	v_lshlrev_b64 v[80:81], 15, v[80:81]
	v_readlane_b32 s1, v253, 8
	v_lshlrev_b32_e32 v0, 2, v200
	v_mov_b32_e32 v143, v1
	v_lshl_add_u64 v[88:89], s[0:1], 0, v[80:81]
	v_lshl_add_u64 v[80:81], v[88:89], 0, v[0:1]
	v_lshl_add_u64 v[86:87], v[80:81], 0, v[142:143]
	global_load_dwordx4 v[82:85], v[86:87], off offset:16
	global_load_dwordx4 v[92:95], v[86:87], off
	v_lshl_add_u32 v0, v195, 2, v181
	s_mov_b32 s0, 0x11000
	v_add3_u32 v107, v0, v166, s0
	v_lshl_add_u32 v0, v194, 2, v199
	v_or_b32_e32 v106, 4, v194
	s_add_i32 s72, s72, s78
	s_cmpk_gt_i32 s72, 0x3ff
	s_cselect_b64 s[38:39], -1, 0
	s_and_b64 vcc, exec, s[38:39]
	s_waitcnt vmcnt(1)
	v_cvt_pk_bf16_f32 v82, v82, v83
	s_waitcnt vmcnt(0)
	v_cvt_pk_bf16_f32 v80, v92, v93
	v_cvt_pk_bf16_f32 v81, v94, v95
	v_cvt_pk_bf16_f32 v83, v84, v85
	global_load_dwordx4 v[92:95], v[86:87], off offset:144
	s_nop 0
	global_load_dwordx4 v[84:87], v[86:87], off offset:128
	s_waitcnt lgkmcnt(0)
	s_barrier
	s_waitcnt vmcnt(0)
	v_cvt_pk_bf16_f32 v84, v84, v85
	v_cvt_pk_bf16_f32 v85, v86, v87
	v_cvt_pk_bf16_f32 v87, v94, v95
	v_cvt_pk_bf16_f32 v86, v92, v93
	ds_read_b128 v[212:215], v171 offset:40960
	ds_read_b128 v[216:219], v172 offset:40960
	ds_read_b128 v[220:223], v169
	ds_read_b128 v[224:227], v168
	ds_read_b128 v[228:231], v169 offset:57344
	ds_read_b128 v[232:235], v168 offset:57344
	ds_read_b128 v[236:239], v180
	ds_read_b128 v[240:243], v176
	ds_read_b128 v[244:247], v180 offset:57344
	ds_read_b128 v[248:251], v176 offset:57344
	s_waitcnt lgkmcnt(4)
	v_mfma_f32_16x16x32_bf16 v[196:199], v[220:223], v[80:83], 0
	v_mfma_f32_16x16x32_bf16 v[196:199], v[224:227], v[84:87], v[196:199]
	v_mfma_f32_16x16x32_bf16 v[196:199], v[228:231], v[212:215], v[196:199]
	v_mfma_f32_16x16x32_bf16 v[196:199], v[232:235], v[216:219], v[196:199]
	ds_read_b128 v[220:223], v178
	ds_read_b128 v[224:227], v175
	ds_read_b128 v[228:231], v178 offset:57344
	ds_read_b128 v[232:235], v175 offset:57344
	s_waitcnt lgkmcnt(4)
	v_mfma_f32_16x16x32_bf16 v[200:203], v[236:239], v[80:83], 0
	v_mfma_f32_16x16x32_bf16 v[200:203], v[240:243], v[84:87], v[200:203]
	v_mfma_f32_16x16x32_bf16 v[200:203], v[244:247], v[212:215], v[200:203]
	v_mfma_f32_16x16x32_bf16 v[200:203], v[248:251], v[216:219], v[200:203]
	ds_read_b128 v[236:239], v121
	ds_read_b128 v[240:243], v120
	ds_read_b128 v[244:247], v121 offset:57344
	ds_read_b128 v[248:251], v120 offset:57344
	s_waitcnt lgkmcnt(4)
	v_mfma_f32_16x16x32_bf16 v[204:207], v[220:223], v[80:83], 0
	v_mfma_f32_16x16x32_bf16 v[204:207], v[224:227], v[84:87], v[204:207]
	v_mfma_f32_16x16x32_bf16 v[204:207], v[228:231], v[212:215], v[204:207]
	v_mfma_f32_16x16x32_bf16 v[204:207], v[232:235], v[216:219], v[204:207]
	s_waitcnt lgkmcnt(0)
	v_mfma_f32_16x16x32_bf16 v[208:211], v[236:239], v[80:83], 0
	v_mfma_f32_16x16x32_bf16 v[208:211], v[240:243], v[84:87], v[208:211]
	v_mfma_f32_16x16x32_bf16 v[208:211], v[244:247], v[212:215], v[208:211]
	v_mfma_f32_16x16x32_bf16 v[208:211], v[248:251], v[216:219], v[208:211]
	v_lshl_add_u32 v93, v194, 10, v107
	v_lshlrev_b32_e32 v92, 6, v192
	ds_read_b128 v[98:101], v169 offset:49152
	ds_read_b128 v[102:105], v171 offset:8192
	ds_read_b128 v[220:223], v168 offset:49152
	ds_read_b128 v[224:227], v172 offset:8192
	s_waitcnt lgkmcnt(2)
	v_mfma_f32_16x16x32_bf16 v[94:97], v[98:101], v[102:105], v[196:199]
	s_waitcnt lgkmcnt(0)
	v_mfma_f32_16x16x32_bf16 v[94:97], v[220:223], v[224:227], v[94:97]
	s_nop 7
	ds_write2st64_b32 v93, v94, v95 offset1:1
	ds_write2st64_b32 v93, v96, v97 offset0:2 offset1:3
	s_waitcnt lgkmcnt(0)
	v_lshl_add_u32 v94, v194, 8, v107
	v_add_u32_e32 v95, v0, v92
	ds_read2st64_b32 v[100:101], v94 offset1:8
	ds_read2_b32 v[102:103], v95 offset1:4
	ds_read2_b32 v[104:105], v95 offset0:8 offset1:12
	s_waitcnt lgkmcnt(1)
	v_mfma_f32_16x16x4_f32 v[96:99], v102, v100, 0
	v_lshl_add_u32 v95, v106, 8, v107
	ds_read_b32 v100, v95
	s_waitcnt lgkmcnt(0)
	v_mfma_f32_16x16x4_f32 v[96:99], v103, v100, v[96:99]
	ds_read_b32 v100, v94 offset:3072
	v_mfma_f32_16x16x4_f32 v[96:99], v104, v101, v[96:99]
	s_waitcnt lgkmcnt(0)
	v_mfma_f32_16x16x4_f32 v[96:99], v105, v100, v[96:99]
	v_cvt_pk_bf16_f32 v96, v96, v97
	v_cvt_pk_bf16_f32 v97, v98, v99
	s_nop 9
	ds_write_b64 v91, v[96:97] offset:8192
	s_waitcnt lgkmcnt(0)
	v_lshl_add_u32 v91, v154, 6, v0
	ds_read_b128 v[100:103], v180 offset:49152
	ds_read_b128 v[104:107], v171 offset:8192
	ds_read_b128 v[220:223], v176 offset:49152
	ds_read_b128 v[224:227], v172 offset:8192
	s_waitcnt lgkmcnt(2)
	v_mfma_f32_16x16x32_bf16 v[96:99], v[100:103], v[104:107], v[200:203]
	s_waitcnt lgkmcnt(0)
	v_mfma_f32_16x16x32_bf16 v[96:99], v[220:223], v[224:227], v[96:99]
	s_nop 7
	ds_write2st64_b32 v93, v96, v97 offset1:1
	ds_write2st64_b32 v93, v98, v99 offset0:2 offset1:3
	s_waitcnt lgkmcnt(0)
	ds_read2st64_b32 v[100:101], v94 offset1:8
	ds_read2_b32 v[102:103], v91 offset1:4
	ds_read2_b32 v[104:105], v91 offset0:8 offset1:12
	s_waitcnt lgkmcnt(1)
	v_mfma_f32_16x16x4_f32 v[96:99], v102, v100, 0
	ds_read_b32 v91, v95
	s_waitcnt lgkmcnt(0)
	v_mfma_f32_16x16x4_f32 v[96:99], v103, v91, v[96:99]
	ds_read_b32 v91, v94 offset:3072
	v_mfma_f32_16x16x4_f32 v[96:99], v104, v101, v[96:99]
	s_waitcnt lgkmcnt(0)
	v_mfma_f32_16x16x4_f32 v[96:99], v105, v91, v[96:99]
	v_cvt_pk_bf16_f32 v96, v96, v97
	v_cvt_pk_bf16_f32 v97, v98, v99
	s_nop 9
	ds_write_b64 v90, v[96:97] offset:8192
	s_waitcnt lgkmcnt(0)
	ds_read_b128 v[100:103], v178 offset:49152
	ds_read_b128 v[104:107], v171 offset:8192
	ds_read_b128 v[220:223], v175 offset:49152
	ds_read_b128 v[224:227], v172 offset:8192
	s_waitcnt lgkmcnt(2)
	v_mfma_f32_16x16x32_bf16 v[96:99], v[100:103], v[104:107], v[204:207]
	s_waitcnt lgkmcnt(0)
	v_mfma_f32_16x16x32_bf16 v[96:99], v[220:223], v[224:227], v[96:99]
	s_nop 7
	ds_write2st64_b32 v93, v96, v97 offset1:1
	ds_write2st64_b32 v93, v98, v99 offset0:2 offset1:3
	s_waitcnt lgkmcnt(0)
	v_lshl_add_u32 v96, v151, 6, v0
	ds_read2st64_b32 v[90:91], v94 offset1:8
	ds_read2_b32 v[100:101], v96 offset1:4
	ds_read2_b32 v[102:103], v96 offset0:8 offset1:12
	s_waitcnt lgkmcnt(1)
	v_mfma_f32_16x16x4_f32 v[96:99], v100, v90, 0
	ds_read_b32 v90, v95
	v_lshl_add_u32 v0, v150, 6, v0
	s_waitcnt lgkmcnt(0)
	v_mfma_f32_16x16x4_f32 v[96:99], v101, v90, v[96:99]
	ds_read_b32 v90, v94 offset:3072
	v_mfma_f32_16x16x4_f32 v[96:99], v102, v91, v[96:99]
	s_waitcnt lgkmcnt(0)
	v_mfma_f32_16x16x4_f32 v[96:99], v103, v90, v[96:99]
	v_cvt_pk_bf16_f32 v90, v96, v97
	v_cvt_pk_bf16_f32 v91, v98, v99
	ds_write_b64 v3, v[90:91] offset:8192
	s_waitcnt lgkmcnt(0)
	s_nop 8
	ds_read_b128 v[84:87], v121 offset:49152
	ds_read_b128 v[96:99], v171 offset:8192
	ds_read_b128 v[220:223], v120 offset:49152
	ds_read_b128 v[224:227], v172 offset:8192
	s_waitcnt lgkmcnt(2)
	v_mfma_f32_16x16x32_bf16 v[80:83], v[84:87], v[96:99], v[208:211]
	s_waitcnt lgkmcnt(0)
	v_mfma_f32_16x16x32_bf16 v[80:83], v[220:223], v[224:227], v[80:83]
	v_mov_b32_e32 v123, 0
	v_lshlrev_b32_e32 v122, 2, v193
	v_lshl_add_u64 v[142:143], v[88:89], 0, v[122:123]
	v_lshlrev_b32_e32 v122, 2, v92
	v_lshl_add_u64 v[142:143], v[142:143], 0, v[122:123]
	global_load_dwordx4 v[196:199], v[142:143], off
	global_load_dwordx4 v[200:203], v[142:143], off offset:16
	global_load_dwordx4 v[204:207], v[142:143], off offset:128
	global_load_dwordx4 v[208:211], v[142:143], off offset:144
	s_mov_b64 s[0:1], 0x1000
	v_lshl_add_u64 v[122:123], v[142:143], 0, s[0:1]
	global_load_dwordx4 v[212:215], v[122:123], off
	global_load_dwordx4 v[216:219], v[122:123], off offset:16
	global_load_dwordx4 v[220:223], v[122:123], off offset:128
	global_load_dwordx4 v[224:227], v[122:123], off offset:144
	s_mov_b64 s[0:1], 0x2000
	v_lshl_add_u64 v[122:123], v[142:143], 0, s[0:1]
	global_load_dwordx4 v[228:231], v[122:123], off
	global_load_dwordx4 v[232:235], v[122:123], off offset:16
	global_load_dwordx4 v[236:239], v[122:123], off offset:128
	global_load_dwordx4 v[240:243], v[122:123], off offset:144
	s_mov_b64 s[0:1], 0x3000
	v_lshl_add_u64 v[122:123], v[142:143], 0, s[0:1]
	global_load_dwordx4 v[244:247], v[122:123], off
	global_load_dwordx4 v[248:251], v[122:123], off offset:16
	global_load_dwordx4 v[116:119], v[122:123], off offset:128
	global_load_dwordx4 v[120:123], v[122:123], off offset:144
	s_nop 7
	ds_write2st64_b32 v93, v80, v81 offset1:1
	ds_write2st64_b32 v93, v82, v83 offset0:2 offset1:3
	s_waitcnt lgkmcnt(0)
	ds_read2st64_b32 v[84:85], v94 offset1:8
	ds_read2_b32 v[86:87], v0 offset1:4
	ds_read2_b32 v[90:91], v0 offset0:8 offset1:12
	s_waitcnt lgkmcnt(1)
	v_mfma_f32_16x16x4_f32 v[80:83], v86, v84, 0
	ds_read_b32 v0, v95
	s_waitcnt lgkmcnt(0)
	v_mfma_f32_16x16x4_f32 v[80:83], v87, v0, v[80:83]
	ds_read_b32 v0, v94 offset:3072
	v_mfma_f32_16x16x4_f32 v[80:83], v90, v85, v[80:83]
	s_waitcnt lgkmcnt(0)
	v_mfma_f32_16x16x4_f32 v[80:83], v91, v0, v[80:83]
	v_cvt_pk_bf16_f32 v80, v80, v81
	v_cvt_pk_bf16_f32 v81, v82, v83
	s_nop 9
	ds_write_b64 v2, v[80:81] offset:8192
	s_waitcnt lgkmcnt(0)
	s_waitcnt lgkmcnt(0)
	s_barrier
	s_waitcnt vmcnt(0)
	s_cbranch_vccnz .LBB0_1048
	v_mov_b32_e32 v80, v177
	s_ashr_i32 s24, s72, 3
	s_lshl_b32 s0, s24, 6
	v_mul_hi_i32 v81, v80, s22
	s_and_b32 s28, s0, s64
	v_lshrrev_b32_e32 v82, 31, v81
	v_ashrrev_i32_e32 v2, 2, v81
	s_add_i32 s28, s28, -1
	v_add_u32_e32 v42, v2, v82
	s_add_i32 s25, s70, s0
	v_add_u32_e32 v2, s28, v42
	s_movk_i32 s0, 0x630
	v_lshlrev_b32_e32 v0, 3, v80
	v_cmp_gt_i32_e32 vcc, s0, v80
	v_cmp_gt_u32_e64 s[0:1], s69, v2
	v_mov_b32_e32 v6, v1
	v_mov_b32_e32 v7, v1
	v_and_b32_e32 v0, 56, v0
	s_and_b64 s[40:41], vcc, s[0:1]
	v_mov_b32_e32 v4, v1
	v_mov_b32_e32 v5, v1
	s_movk_i32 s0, 0xffe8
	v_mov_b64_e32 v[10:11], v[6:7]
	s_and_b32 s5, s71, 0x1c0
	v_mul_lo_u32 v43, v42, s0
	v_lshlrev_b32_e32 v40, 1, v0
	v_mov_b64_e32 v[8:9], v[4:5]
	s_and_saveexec_b64 s[0:1], s[40:41]
	s_cbranch_execz .LBB0_1037
	v_add_u32_e32 v0, s25, v42
	v_mov_b64_e32 v[2:3], s[16:17]
	v_mad_i64_i32 v[2:3], s[40:41], v0, s12, v[2:3]
	v_add_lshl_u32 v0, v43, v80, 6
	v_and_b32_e32 v8, 0xfffffe00, v0
	v_ashrrev_i32_e32 v9, 31, v8
	v_lshl_add_u64 v[2:3], v[8:9], 1, v[2:3]
	s_lshl_b32 s10, s5, 1
	v_lshl_add_u64 v[2:3], v[2:3], 0, s[10:11]
	v_mov_b32_e32 v41, v1
	v_lshl_add_u64 v[2:3], v[2:3], 0, v[40:41]
	v_add_co_u32_e32 v2, vcc, 0x1000, v2
	s_nop 1
	v_addc_co_u32_e32 v3, vcc, 0, v3, vcc
	global_load_dwordx4 v[8:11], v[2:3], off offset:1024

.LBB0_1048:
	ds_read_b128 v[108:111], v171 offset:24576
	ds_read_b128 v[112:115], v172 offset:24576
	ds_read_b128 v[96:99], v171 offset:32768
	ds_read_b128 v[92:95], v172 offset:32768
	ds_read_b128 v[88:91], v171 offset:16384
	ds_read_b128 v[170:173], v172 offset:16384
	v_cvt_pk_bf16_f32 v196, v196, v197
	v_cvt_pk_bf16_f32 v197, v198, v199
	v_cvt_pk_bf16_f32 v198, v200, v201
	v_cvt_pk_bf16_f32 v199, v202, v203
	v_cvt_pk_bf16_f32 v204, v204, v205
	v_cvt_pk_bf16_f32 v205, v206, v207
	v_cvt_pk_bf16_f32 v206, v208, v209
	v_cvt_pk_bf16_f32 v207, v210, v211
	v_cvt_pk_bf16_f32 v212, v212, v213
	v_cvt_pk_bf16_f32 v213, v214, v215
	v_cvt_pk_bf16_f32 v214, v216, v217
	v_cvt_pk_bf16_f32 v215, v218, v219
	v_cvt_pk_bf16_f32 v220, v220, v221
	v_cvt_pk_bf16_f32 v221, v222, v223
	v_cvt_pk_bf16_f32 v222, v224, v225
	v_cvt_pk_bf16_f32 v223, v226, v227
	ds_read_b128 v[200:203], v169 offset:40960
	ds_read_b128 v[208:211], v168 offset:40960
	ds_read_b128 v[216:219], v169 offset:8192
	ds_read_b128 v[224:227], v168 offset:8192
	v_cvt_pk_bf16_f32 v228, v228, v229
	v_cvt_pk_bf16_f32 v229, v230, v231
	v_cvt_pk_bf16_f32 v230, v232, v233
	v_cvt_pk_bf16_f32 v231, v234, v235
	v_cvt_pk_bf16_f32 v236, v236, v237
	v_cvt_pk_bf16_f32 v237, v238, v239
	v_cvt_pk_bf16_f32 v238, v240, v241
	v_cvt_pk_bf16_f32 v239, v242, v243
	v_cvt_pk_bf16_f32 v244, v244, v245
	v_cvt_pk_bf16_f32 v245, v246, v247
	v_cvt_pk_bf16_f32 v246, v248, v249
	v_cvt_pk_bf16_f32 v247, v250, v251
	v_cvt_pk_bf16_f32 v116, v116, v117
	v_cvt_pk_bf16_f32 v117, v118, v119
	v_cvt_pk_bf16_f32 v118, v120, v121
	v_cvt_pk_bf16_f32 v119, v122, v123
	ds_read_b128 v[232:235], v169 offset:43008
	ds_read_b128 v[240:243], v168 offset:43008
	ds_read_b128 v[248:251], v169 offset:10240
	ds_read_b128 v[120:123], v168 offset:10240
	s_waitcnt lgkmcnt(4)
	v_mfma_f32_16x16x32_bf16 v[80:83], v[108:111], v[196:199], 0
	v_mfma_f32_16x16x32_bf16 v[80:83], v[112:115], v[204:207], v[80:83]
	v_mfma_f32_16x16x32_bf16 v[80:83], v[96:99], v[200:203], v[80:83]
	v_mfma_f32_16x16x32_bf16 v[80:83], v[92:95], v[208:211], v[80:83]
	v_mfma_f32_16x16x32_bf16 v[80:83], v[88:91], v[216:219], v[80:83]
	v_mfma_f32_16x16x32_bf16 v[80:83], v[170:173], v[224:227], v[80:83]
	ds_read_b128 v[200:203], v169 offset:45056
	ds_read_b128 v[208:211], v168 offset:45056
	ds_read_b128 v[216:219], v169 offset:12288
	ds_read_b128 v[224:227], v168 offset:12288
	s_waitcnt lgkmcnt(4)
	v_mfma_f32_16x16x32_bf16 v[100:103], v[108:111], v[212:215], 0
	v_mfma_f32_16x16x32_bf16 v[100:103], v[112:115], v[220:223], v[100:103]
	v_mfma_f32_16x16x32_bf16 v[100:103], v[96:99], v[232:235], v[100:103]
	v_mfma_f32_16x16x32_bf16 v[100:103], v[92:95], v[240:243], v[100:103]
	v_mfma_f32_16x16x32_bf16 v[100:103], v[88:91], v[248:251], v[100:103]
	v_mfma_f32_16x16x32_bf16 v[100:103], v[170:173], v[120:123], v[100:103]
	ds_read_b128 v[232:235], v169 offset:47104
	ds_read_b128 v[240:243], v168 offset:47104
	ds_read_b128 v[248:251], v169 offset:14336
	ds_read_b128 v[120:123], v168 offset:14336
	s_waitcnt lgkmcnt(4)
	v_mfma_f32_16x16x32_bf16 v[104:107], v[108:111], v[228:231], 0
	v_mfma_f32_16x16x32_bf16 v[104:107], v[112:115], v[236:239], v[104:107]
	v_mfma_f32_16x16x32_bf16 v[104:107], v[96:99], v[200:203], v[104:107]
	v_mfma_f32_16x16x32_bf16 v[104:107], v[92:95], v[208:211], v[104:107]
	v_mfma_f32_16x16x32_bf16 v[104:107], v[88:91], v[216:219], v[104:107]
	v_mfma_f32_16x16x32_bf16 v[104:107], v[170:173], v[224:227], v[104:107]
	s_waitcnt lgkmcnt(0)
	v_mfma_f32_16x16x32_bf16 v[84:87], v[108:111], v[244:247], 0
	v_mfma_f32_16x16x32_bf16 v[84:87], v[112:115], v[116:119], v[84:87]
	v_mfma_f32_16x16x32_bf16 v[84:87], v[96:99], v[232:235], v[84:87]
	v_mfma_f32_16x16x32_bf16 v[84:87], v[92:95], v[240:243], v[84:87]
	v_mfma_f32_16x16x32_bf16 v[84:87], v[88:91], v[248:251], v[84:87]
	v_mfma_f32_16x16x32_bf16 v[84:87], v[170:173], v[120:123], v[84:87]
	s_mov_b64 s[0:1], 0x3080
	s_movk_i32 s0, 0xff84
	v_mad_i32_i24 v0, v192, s0, v167
	v_cndmask_b32_e64 v2, v158, v144, s[36:37]
	v_lshl_add_u32 v2, v2, 8, v0
	v_cndmask_b32_e64 v3, v159, v145, s[36:37]
	v_lshl_add_u32 v3, v3, 8, v0
	v_add_u32_e32 v2, 0xc000, v2
	v_add_u32_e32 v3, 0xc000, v3
	v_cndmask_b32_e64 v88, v164, v146, s[36:37]
	v_cndmask_b32_e64 v89, v165, v147, s[36:37]
	v_lshl_add_u32 v88, v88, 8, v0
	v_lshl_add_u32 v0, v89, 8, v0
	s_barrier
	ds_write2_b32 v2, v80, v100 offset1:16
	v_add_u32_e32 v80, 0xc000, v88
	v_add_u32_e32 v0, 0xc000, v0
	ds_write2_b32 v3, v81, v101 offset1:16
	ds_write2_b32 v80, v82, v102 offset1:16
	ds_write2_b32 v0, v83, v103 offset1:16
	ds_write2_b32 v2, v104, v84 offset0:32 offset1:48
	ds_write2_b32 v3, v105, v85 offset0:32 offset1:48
	ds_write2_b32 v80, v106, v86 offset0:32 offset1:48
	ds_write2_b32 v0, v107, v87 offset0:32 offset1:48
	s_waitcnt lgkmcnt(0)
	s_barrier
	s_and_saveexec_b64 s[40:41], s[36:37]
	s_cbranch_execz .LBB0_819
	v_lshlrev_b32_e32 v0, 6, v144
	v_or_b32_e32 v2, v0, v192
	v_lshlrev_b32_e32 v3, 2, v2
	v_add_u32_e32 v2, 0, v3
	v_add_u32_e32 v3, s30, v3
	ds_read_b32 v2, v2 offset:49152
	ds_read_b32 v86, v3
	ds_read_b32 v114, v148 offset:49344
	v_or_b32_e32 v3, v152, v192
	v_lshlrev_b32_e32 v3, 2, v3
	v_add_u32_e32 v80, 0, v3
	v_add_u32_e32 v3, s30, v3
	ds_read_b32 v80, v80 offset:49152
	ds_read_b32 v88, v3
	v_or_b32_e32 v3, v155, v192
	v_lshlrev_b32_e32 v3, 2, v3
	v_add_u32_e32 v81, 0, v3
	v_add_u32_e32 v3, s30, v3
	ds_read_b32 v82, v81 offset:49152
	ds_read_b32 v90, v3
	v_or_b32_e32 v3, v157, v192
	v_lshlrev_b32_e32 v3, 2, v3
	v_add_u32_e32 v81, 0, v3
	v_add_u32_e32 v3, s30, v3
	ds_read_b32 v84, v81 offset:49152
	ds_read_b32 v92, v3
	v_or_b32_e32 v3, v0, v154
	v_lshl_add_u32 v3, v3, 2, s30
	ds_read_b32 v87, v3
	ds_read_b32 v116, v149 offset:49344
	v_or_b32_e32 v3, v152, v154
	v_lshl_add_u32 v3, v3, 2, s30
	ds_read_b32 v89, v3
	ds_read_b32 v110, v153 offset:49344
	v_or_b32_e32 v3, v155, v154
	v_lshl_add_u32 v3, v3, 2, s30
	ds_read_b32 v91, v3
	ds_read_b32 v100, v156 offset:49344
	v_or_b32_e32 v3, v157, v154
	v_lshl_add_u32 v3, v3, 2, s30
	ds_read_b32 v93, v3
	v_or_b32_e32 v3, v0, v151
	v_or_b32_e32 v0, v0, v150
	v_lshl_add_u32 v0, v0, 2, s30
	ds_read_b32 v106, v0
	v_or_b32_e32 v0, v152, v150
	v_lshl_add_u32 v3, v3, 2, s30
	v_lshl_add_u32 v0, v0, 2, s30
	ds_read_b32 v107, v3
	ds_read_b32 v112, v0
	v_or_b32_e32 v3, v152, v151
	v_or_b32_e32 v0, v155, v150
	v_lshl_add_u32 v3, v3, 2, s30
	v_lshl_add_u32 v0, v0, 2, s30
	ds_read_b32 v113, v3
	ds_read_b32 v102, v0
	v_or_b32_e32 v3, v155, v151
	v_or_b32_e32 v0, v157, v150
	v_lshl_add_u32 v3, v3, 2, s30
	v_lshl_add_u32 v0, v0, 2, s30
	ds_read_b32 v103, v3
	ds_read_b32 v96, v0
	v_or_b32_e32 v3, v157, v151
	v_lshl_add_u32 v3, v3, 2, s30
	ds_read_b32 v97, v3
	v_and_b32_e32 v3, 64, v179
	v_xor_b32_e32 v0, 1, v179
	v_add_u32_e32 v3, 64, v3
	v_cmp_lt_i32_e32 vcc, v0, v3
	v_add_u32_e32 v81, 0xc000, v148
	ds_read2_b32 v[104:105], v81 offset0:16 offset1:32
	v_cndmask_b32_e32 v0, v179, v0, vcc
	v_lshlrev_b32_e32 v118, 2, v0
	v_xor_b32_e32 v0, 2, v179
	v_cmp_lt_i32_e32 vcc, v0, v3
	s_waitcnt lgkmcnt(0)
	v_mov_b32_e32 v115, v105
	v_add_u32_e32 v81, 0xc000, v149
	v_cndmask_b32_e32 v0, v179, v0, vcc
	v_lshlrev_b32_e32 v119, 2, v0
	v_xor_b32_e32 v0, 4, v179
	v_cmp_lt_i32_e32 vcc, v0, v3
	v_pk_add_f32 v[114:115], v[114:115], v[106:107]
	ds_read2_b32 v[108:109], v81 offset0:16 offset1:32
	v_cndmask_b32_e32 v0, v179, v0, vcc
	v_lshlrev_b32_e32 v120, 2, v0
	v_xor_b32_e32 v0, 8, v179
	v_cmp_lt_i32_e32 vcc, v0, v3
	v_mov_b32_e32 v3, v104
	v_pk_add_f32 v[2:3], v[2:3], v[86:87]
	v_cndmask_b32_e32 v0, v179, v0, vcc
	v_lshlrev_b32_e32 v121, 2, v0
	v_add_f32_e32 v0, 0, v2
	v_add_f32_e32 v0, v0, v3
	v_add_u32_e32 v81, 0xc000, v153
	v_add_f32_e32 v0, v0, v115
	ds_read2_b32 v[98:99], v81 offset0:16 offset1:32
	v_add_u32_e32 v81, 0xc000, v156
	v_add_f32_e32 v0, v0, v114
	ds_read2_b32 v[94:95], v81 offset0:16 offset1:32
	s_nop 1
	v_mov_b32_dpp v81, v0 quad_perm:[1,0,3,2] row_mask:0xf bank_mask:0xf
	s_waitcnt lgkmcnt(2)
	v_mov_b32_e32 v117, v109
	v_pk_add_f32 v[112:113], v[116:117], v[112:113]
	s_waitcnt lgkmcnt(1)
	v_mov_b32_e32 v111, v99
	v_pk_add_f32 v[102:103], v[110:111], v[102:103]
	s_waitcnt lgkmcnt(0)
	v_add_f32_e32 v0, v0, v81
	s_nop 1
	v_mov_b32_dpp v81, v0 quad_perm:[2,3,0,1] row_mask:0xf bank_mask:0xf
	v_mov_b32_e32 v101, v95
	v_pk_add_f32 v[96:97], v[100:101], v[96:97]
	s_mov_b32 s0, 0x3a27c5ac
	s_mov_b32 s6, 0x3c800000
	s_waitcnt lgkmcnt(0)
	v_add_f32_e32 v0, v0, v81
	s_nop 1
	v_mov_b32_dpp v81, v0 row_shl:4 row_mask:0xf bank_mask:0x5
	s_nop 1
	v_mov_b32_dpp v81, v0 row_shr:4 row_mask:0xf bank_mask:0xa
	v_readlane_b32 s44, v252, 35
	v_readlane_b32 s45, v252, 36
	v_readlane_b32 s46, v252, 37
	v_readlane_b32 s47, v252, 38
	s_waitcnt lgkmcnt(0)
	v_add_f32_e32 v0, v0, v81
	s_nop 1
	v_mov_b32_dpp v81, v0 row_shl:8 row_mask:0xf bank_mask:0x3
	s_nop 1
	v_mov_b32_dpp v81, v0 row_shr:8 row_mask:0xf bank_mask:0xc
	v_readlane_b32 s48, v252, 39
	v_readlane_b32 s49, v252, 40
	v_readlane_b32 s50, v252, 41
	v_readlane_b32 s51, v252, 42
	s_waitcnt lgkmcnt(0)
	v_add_f32_e32 v0, v0, v81
	v_mov_b32_e32 v81, v108
	v_mul_f32_e32 v0, 0x3c800000, v0
	v_pk_add_f32 v[80:81], v[80:81], v[88:89]
	v_pk_add_f32 v[86:87], v[2:3], v[0:1] op_sel_hi:[1,0] neg_lo:[0,1] neg_hi:[0,1]
	v_pk_add_f32 v[2:3], v[114:115], v[0:1] op_sel_hi:[1,0] neg_lo:[0,1] neg_hi:[0,1]
	v_add_f32_e32 v0, 0, v80
	v_add_f32_e32 v0, v0, v81
	v_add_f32_e32 v0, v0, v113
	v_add_f32_e32 v0, v0, v112
	s_nop 1
	v_mov_b32_dpp v83, v0 quad_perm:[1,0,3,2] row_mask:0xf bank_mask:0xf
	v_pk_mul_f32 v[106:107], v[86:87], v[86:87]
	v_pk_mul_f32 v[104:105], v[2:3], v[2:3]
	v_mov_b32_e32 v101, v106
	v_readlane_b32 s52, v252, 43
	s_waitcnt lgkmcnt(0)
	v_add_f32_e32 v0, v0, v83
	s_nop 1
	v_mov_b32_dpp v83, v0 quad_perm:[2,3,0,1] row_mask:0xf bank_mask:0xf
	v_readlane_b32 s53, v252, 44
	v_readlane_b32 s54, v252, 45
	v_readlane_b32 s55, v252, 46
	v_readlane_b32 s56, v252, 47
	s_waitcnt lgkmcnt(0)
	v_add_f32_e32 v0, v0, v83
	s_nop 1
	v_mov_b32_dpp v83, v0 row_shl:4 row_mask:0xf bank_mask:0x5
	s_nop 1
	v_mov_b32_dpp v83, v0 row_shr:4 row_mask:0xf bank_mask:0xa
	v_readlane_b32 s57, v252, 48
	s_mov_b64 s[44:45], s[48:49]
	s_mov_b64 s[46:47], s[50:51]
	s_mov_b64 s[48:49], s[52:53]
	s_waitcnt lgkmcnt(0)
	v_add_f32_e32 v0, v0, v83
	s_nop 1
	v_mov_b32_dpp v83, v0 row_shl:8 row_mask:0xf bank_mask:0x3
	s_nop 1
	v_mov_b32_dpp v83, v0 row_shr:8 row_mask:0xf bank_mask:0xc
	s_mov_b64 s[50:51], s[54:55]
	s_mov_b64 s[52:53], s[56:57]
	v_readlane_b32 s5, v254, 59
	s_lshl_b32 s4, s4, 6
	s_waitcnt lgkmcnt(0)
	v_add_f32_e32 v0, v0, v83
	v_mov_b32_e32 v83, v98
	v_mul_f32_e32 v0, 0x3c800000, v0
	v_pk_add_f32 v[82:83], v[82:83], v[90:91]
	v_pk_add_f32 v[88:89], v[80:81], v[0:1] op_sel_hi:[1,0] neg_lo:[0,1] neg_hi:[0,1]
	v_pk_add_f32 v[80:81], v[112:113], v[0:1] op_sel_hi:[1,0] neg_lo:[0,1] neg_hi:[0,1]
	v_add_f32_e32 v0, 0, v82
	v_add_f32_e32 v0, v0, v83
	v_add_f32_e32 v0, v0, v103
	v_add_f32_e32 v0, v0, v102
	s_nop 1
	v_mov_b32_dpp v85, v0 quad_perm:[1,0,3,2] row_mask:0xf bank_mask:0xf
	v_pk_mul_f32 v[108:109], v[88:89], v[88:89]
	v_pk_mul_f32 v[112:113], v[80:81], v[80:81]
	v_mov_b32_e32 v100, v108
	v_mov_b32_e32 v106, v109
	s_waitcnt lgkmcnt(0)
	v_add_f32_e32 v0, v0, v85
	s_nop 1
	v_mov_b32_dpp v85, v0 quad_perm:[2,3,0,1] row_mask:0xf bank_mask:0xf
	v_pk_add_f32 v[100:101], v[100:101], v[106:107]
	s_add_i32 s4, s4, s63
	v_readlane_b32 s58, v252, 49
	v_readlane_b32 s59, v252, 50
	s_waitcnt lgkmcnt(0)
	v_add_f32_e32 v0, v0, v85
	s_nop 1
	v_mov_b32_dpp v85, v0 row_shl:4 row_mask:0xf bank_mask:0x5
	s_nop 1
	v_mov_b32_dpp v85, v0 row_shr:4 row_mask:0xf bank_mask:0xa
	s_waitcnt lgkmcnt(0)
	v_add_f32_e32 v0, v0, v85
	s_nop 1
	v_mov_b32_dpp v85, v0 row_shl:8 row_mask:0xf bank_mask:0x3
	s_nop 1
	v_mov_b32_dpp v85, v0 row_shr:8 row_mask:0xf bank_mask:0xc
	s_waitcnt lgkmcnt(0)
	v_add_f32_e32 v0, v0, v85
	v_mov_b32_e32 v85, v94
	v_mul_f32_e32 v0, 0x3c800000, v0
	v_pk_add_f32 v[84:85], v[84:85], v[92:93]
	v_pk_add_f32 v[90:91], v[82:83], v[0:1] op_sel_hi:[1,0] neg_lo:[0,1] neg_hi:[0,1]
	v_pk_add_f32 v[82:83], v[102:103], v[0:1] op_sel_hi:[1,0] neg_lo:[0,1] neg_hi:[0,1]
	v_add_f32_e32 v0, 0, v84
	v_add_f32_e32 v0, v0, v85
	v_mov_b32_e32 v102, v113
	v_mov_b32_e32 v103, v105
	v_add_f32_e32 v0, v0, v97
	v_pk_add_f32 v[100:101], v[102:103], v[100:101]
	v_mov_b32_e32 v113, v104
	v_add_f32_e32 v0, v0, v96
	v_pk_add_f32 v[100:101], v[112:113], v[100:101]
	s_nop 1
	v_mov_b32_dpp v92, v0 quad_perm:[1,0,3,2] row_mask:0xf bank_mask:0xf
	s_nop 1
	v_mov_b32_dpp v103, v101 quad_perm:[1,0,3,2] row_mask:0xf bank_mask:0xf
	s_nop 1
	v_mov_b32_dpp v102, v100 quad_perm:[1,0,3,2] row_mask:0xf bank_mask:0xf
	v_mov_b64_e32 v[104:105], s[0:1]
	v_pk_mul_f32 v[98:99], v[90:91], v[90:91]
	s_waitcnt lgkmcnt(0)
	v_add_f32_e32 v0, v0, v92
	s_nop 1
	v_mov_b32_dpp v92, v0 quad_perm:[2,3,0,1] row_mask:0xf bank_mask:0xf
	s_waitcnt lgkmcnt(0)
	v_pk_add_f32 v[100:101], v[100:101], v[102:103]
	s_nop 1
	v_mov_b32_dpp v103, v101 quad_perm:[2,3,0,1] row_mask:0xf bank_mask:0xf
	s_nop 1
	v_mov_b32_dpp v102, v100 quad_perm:[2,3,0,1] row_mask:0xf bank_mask:0xf
	v_pk_mul_f32 v[110:111], v[82:83], v[82:83]
	s_waitcnt lgkmcnt(0)
	v_add_f32_e32 v0, v0, v92
	s_nop 1
	v_mov_b32_dpp v92, v0 row_shl:4 row_mask:0xf bank_mask:0x5
	s_nop 1
	v_mov_b32_dpp v92, v0 row_shr:4 row_mask:0xf bank_mask:0xa
	s_waitcnt lgkmcnt(0)
	v_pk_add_f32 v[100:101], v[100:101], v[102:103]
	s_nop 1
	v_mov_b32_dpp v103, v101 row_shl:4 row_mask:0xf bank_mask:0x5
	s_nop 1
	v_mov_b32_dpp v103, v101 row_shr:4 row_mask:0xf bank_mask:0xa
	s_nop 1
	v_mov_b32_dpp v102, v100 row_shl:4 row_mask:0xf bank_mask:0x5
	s_nop 1
	v_mov_b32_dpp v102, v100 row_shr:4 row_mask:0xf bank_mask:0xa
	s_waitcnt lgkmcnt(0)
	v_add_f32_e32 v0, v0, v92
	s_nop 1
	v_mov_b32_dpp v92, v0 row_shl:8 row_mask:0xf bank_mask:0x3
	s_nop 1
	v_mov_b32_dpp v92, v0 row_shr:8 row_mask:0xf bank_mask:0xc
	s_waitcnt lgkmcnt(0)
	v_pk_add_f32 v[100:101], v[100:101], v[102:103]
	s_nop 1
	v_mov_b32_dpp v103, v101 row_shl:8 row_mask:0xf bank_mask:0x3
	s_nop 1
	v_mov_b32_dpp v103, v101 row_shr:8 row_mask:0xf bank_mask:0xc
	s_nop 1
	v_mov_b32_dpp v102, v100 row_shl:8 row_mask:0xf bank_mask:0x3
	s_nop 1
	v_mov_b32_dpp v102, v100 row_shr:8 row_mask:0xf bank_mask:0xc
	s_waitcnt lgkmcnt(0)
	v_add_f32_e32 v0, v0, v92
	v_mul_f32_e32 v0, 0x3c800000, v0
	v_pk_add_f32 v[92:93], v[84:85], v[0:1] op_sel_hi:[1,0] neg_lo:[0,1] neg_hi:[0,1]
	v_pk_add_f32 v[84:85], v[96:97], v[0:1] op_sel_hi:[1,0] neg_lo:[0,1] neg_hi:[0,1]
	s_waitcnt lgkmcnt(0)
	v_pk_add_f32 v[100:101], v[100:101], v[102:103]
	v_pk_mul_f32 v[94:95], v[92:93], v[92:93]
	v_pk_fma_f32 v[100:101], v[100:101], s[6:7], v[104:105] op_sel_hi:[1,0,0]
	v_pk_mul_f32 v[96:97], v[84:85], v[84:85]
	v_mul_f32_e32 v0, 0x4b800000, v101
	v_cmp_gt_f32_e64 s[0:1], s29, v101
	v_cmp_gt_f32_e32 vcc, s29, v100
	s_nop 0
	v_cndmask_b32_e64 v0, v101, v0, s[0:1]
	v_rsq_f32_e32 v0, v0
	s_nop 0
	v_mul_f32_e32 v101, 0x45800000, v0
	v_cndmask_b32_e64 v103, v0, v101, s[0:1]
	v_mul_f32_e32 v0, 0x4b800000, v100
	v_cndmask_b32_e32 v0, v100, v0, vcc
	v_rsq_f32_e32 v0, v0
	v_mov_b32_e32 v101, v98
	v_mov_b32_e32 v98, v95
	v_mul_f32_e32 v86, v86, v103
	v_mul_f32_e32 v100, 0x45800000, v0
	v_cndmask_b32_e32 v102, v0, v100, vcc
	v_mov_b32_e32 v100, v94
	v_pk_add_f32 v[94:95], v[100:101], v[98:99]
	global_load_dword v100, v190, s[50:51]
	global_load_dword v101, v190, s[52:53]
	v_mov_b32_e32 v98, v97
	v_mov_b32_e32 v99, v111
	v_pk_add_f32 v[94:95], v[98:99], v[94:95]
	v_mov_b32_e32 v97, v110
	v_pk_add_f32 v[94:95], v[96:97], v[94:95]
	s_nop 1
	v_mov_b32_dpp v97, v95 quad_perm:[1,0,3,2] row_mask:0xf bank_mask:0xf
	s_nop 1
	v_mov_b32_dpp v96, v94 quad_perm:[1,0,3,2] row_mask:0xf bank_mask:0xf
	v_mul_f32_e32 v3, v3, v103
	v_mul_f32_e32 v2, v2, v103
	s_waitcnt lgkmcnt(0)
	v_pk_add_f32 v[94:95], v[94:95], v[96:97]
	s_nop 1
	v_mov_b32_dpp v97, v95 quad_perm:[2,3,0,1] row_mask:0xf bank_mask:0xf
	s_nop 1
	v_mov_b32_dpp v96, v94 quad_perm:[2,3,0,1] row_mask:0xf bank_mask:0xf
	s_waitcnt lgkmcnt(0)
	v_pk_add_f32 v[94:95], v[94:95], v[96:97]
	s_nop 1
	v_mov_b32_dpp v97, v95 row_shl:4 row_mask:0xf bank_mask:0x5
	s_nop 1
	v_mov_b32_dpp v97, v95 row_shr:4 row_mask:0xf bank_mask:0xa
	s_nop 1
	v_mov_b32_dpp v96, v94 row_shl:4 row_mask:0xf bank_mask:0x5
	s_nop 1
	v_mov_b32_dpp v96, v94 row_shr:4 row_mask:0xf bank_mask:0xa
	s_waitcnt lgkmcnt(0)
	v_pk_add_f32 v[94:95], v[94:95], v[96:97]
	s_nop 1
	v_mov_b32_dpp v97, v95 row_shl:8 row_mask:0xf bank_mask:0x3
	s_nop 1
	v_mov_b32_dpp v97, v95 row_shr:8 row_mask:0xf bank_mask:0xc
	s_nop 1
	v_mov_b32_dpp v96, v94 row_shl:8 row_mask:0xf bank_mask:0x3
	s_nop 1
	v_mov_b32_dpp v96, v94 row_shr:8 row_mask:0xf bank_mask:0xc
	s_waitcnt lgkmcnt(0)
	v_pk_add_f32 v[94:95], v[94:95], v[96:97]
	s_nop 0
	v_pk_fma_f32 v[94:95], v[94:95], s[6:7], v[104:105] op_sel_hi:[1,0,0]
	s_waitcnt vmcnt(0)
	v_fma_f32 v86, v86, v100, v101
	v_mul_f32_e32 v0, 0x4b800000, v95
	v_cmp_gt_f32_e64 s[0:1], s29, v95
	v_cmp_gt_f32_e32 vcc, s29, v94
	s_nop 0
	v_cndmask_b32_e64 v0, v95, v0, s[0:1]
	v_rsq_f32_e32 v0, v0
	s_nop 0
	v_mul_f32_e32 v95, 0x45800000, v0
	v_cndmask_b32_e64 v105, v0, v95, s[0:1]
	v_mul_f32_e32 v0, 0x4b800000, v94
	v_cndmask_b32_e32 v0, v94, v0, vcc
	v_rsq_f32_e32 v0, v0
	v_readlane_b32 s0, v254, 38
	v_readlane_b32 s1, v254, 39
	v_mul_f32_e32 v94, 0x45800000, v0
	v_cndmask_b32_e32 v104, v0, v94, vcc
	v_lshl_add_u32 v94, v144, 2, s5
	ds_read_b32 v106, v94
	v_or_b32_e32 v94, s4, v144
	v_lshlrev_b32_e32 v0, 1, v191
	v_ashrrev_i32_e32 v95, 31, v94
	v_lshl_add_u64 v[108:109], s[0:1], 0, v[0:1]
	s_waitcnt lgkmcnt(0)
	v_fmac_f32_e32 v86, v126, v106
	v_mul_f32_e32 v68, v68, v86
	v_lshlrev_b64 v[94:95], 11, v[94:95]
	v_cvt_pk_bf16_f32 v68, v68, v68
	v_lshl_add_u64 v[96:97], v[108:109], 0, v[94:95]
	v_lshl_add_u32 v86, v145, 2, s5
	global_store_short v[96:97], v68, off
	v_mul_f32_e32 v68, v88, v102
	ds_read_b32 v88, v86
	v_fma_f32 v68, v100, v68, v101
	s_waitcnt lgkmcnt(0)
	v_fmac_f32_e32 v68, v140, v88
	v_mul_f32_e32 v68, v69, v68
	v_cvt_pk_bf16_f32 v86, v68, v68
	v_or_b32_e32 v68, s4, v145
	v_ashrrev_i32_e32 v69, 31, v68
	v_lshlrev_b64 v[96:97], 11, v[68:69]
	v_lshl_add_u64 v[68:69], v[108:109], 0, v[96:97]
	global_store_short v[68:69], v86, off
	v_lshl_add_u32 v69, v146, 2, s5
	v_mul_f32_e32 v68, v90, v105
	ds_read_b32 v90, v69
	v_fma_f32 v68, v100, v68, v101
	s_waitcnt lgkmcnt(0)
	v_fmac_f32_e32 v68, v141, v90
	v_mul_f32_e32 v68, v70, v68
	v_cvt_pk_bf16_f32 v70, v68, v68
	v_or_b32_e32 v68, s4, v146
	v_ashrrev_i32_e32 v69, 31, v68
	v_lshlrev_b64 v[98:99], 11, v[68:69]
	v_lshl_add_u64 v[68:69], v[108:109], 0, v[98:99]
	global_store_short v[68:69], v70, off
	v_mul_f32_e32 v68, v92, v104
	v_fmac_f32_e32 v101, v100, v68
	v_lshl_add_u32 v68, v147, 2, s5
	ds_read_b32 v92, v68
	s_waitcnt lgkmcnt(0)
	v_fmac_f32_e32 v101, v129, v92
	v_mul_f32_e32 v68, v71, v101
	v_cvt_pk_bf16_f32 v70, v68, v68
	v_or_b32_e32 v68, s4, v147
	v_ashrrev_i32_e32 v69, 31, v68
	v_lshlrev_b64 v[100:101], 11, v[68:69]
	v_lshl_add_u64 v[68:69], v[108:109], 0, v[100:101]
	global_store_short v[68:69], v70, off
	global_load_dword v107, v190, s[50:51] offset:64
	global_load_dword v108, v190, s[52:53] offset:64
	v_mul_f32_e32 v68, v87, v103
	v_lshl_add_u64 v[86:87], s[0:1], 0, v[96:97]
	s_waitcnt vmcnt(0)
	v_fma_f32 v68, v68, v107, v108
	v_fmac_f32_e32 v68, v128, v106
	v_mul_f32_e32 v64, v64, v68
	v_lshl_add_u64 v[68:69], s[0:1], 0, v[94:95]
	v_or_b32_e32 v94, 32, v0
	v_mov_b32_e32 v95, v1
	v_cvt_pk_bf16_f32 v64, v64, v64
	v_lshl_add_u64 v[70:71], v[68:69], 0, v[94:95]
	global_store_short v[70:71], v64, off
	v_mul_f32_e32 v64, v89, v102
	v_fma_f32 v64, v64, v107, v108
	v_fmac_f32_e32 v64, v138, v88
	v_mul_f32_e32 v64, v65, v64
	v_cvt_pk_bf16_f32 v70, v64, v64
	v_lshl_add_u64 v[64:65], v[86:87], 0, v[94:95]
	global_store_short v[64:65], v70, off
	v_mul_f32_e32 v64, v91, v105
	v_fma_f32 v64, v64, v107, v108
	v_fmac_f32_e32 v64, v139, v90
	v_mul_f32_e32 v64, v66, v64
	v_lshl_add_u64 v[70:71], s[0:1], 0, v[98:99]
	v_cvt_pk_bf16_f32 v66, v64, v64
	v_lshl_add_u64 v[64:65], v[70:71], 0, v[94:95]
	global_store_short v[64:65], v66, off
	v_mul_f32_e32 v64, v93, v104
	v_fmac_f32_e32 v108, v64, v107
	v_fmac_f32_e32 v108, v131, v92
	v_mul_f32_e32 v64, v67, v108
	v_cvt_pk_bf16_f32 v89, v64, v64
	v_lshl_add_u64 v[64:65], s[0:1], 0, v[100:101]
	v_lshl_add_u64 v[66:67], v[64:65], 0, v[94:95]
	global_store_short v[66:67], v89, off
	global_load_dword v89, v190, s[50:51] offset:128
	s_nop 0
	global_load_dword v91, v190, s[52:53] offset:128
	v_or_b32_e32 v66, 64, v0
	v_mov_b32_e32 v67, v1
	v_lshl_add_u64 v[94:95], v[68:69], 0, v[66:67]
	v_or_b32_e32 v0, 0x60, v0
	s_waitcnt vmcnt(0)
	v_fma_f32 v3, v3, v89, v91
	v_fmac_f32_e32 v3, v130, v106
	v_mul_f32_e32 v3, v72, v3
	v_cvt_pk_bf16_f32 v3, v3, v3
	global_store_short v[94:95], v3, off
	v_mul_f32_e32 v3, v81, v102
	v_fma_f32 v3, v3, v89, v91
	v_fmac_f32_e32 v3, v136, v88
	v_mul_f32_e32 v3, v73, v3
	v_cvt_pk_bf16_f32 v3, v3, v3
	v_lshl_add_u64 v[72:73], v[86:87], 0, v[66:67]
	global_store_short v[72:73], v3, off
	v_mul_f32_e32 v3, v83, v105
	v_fma_f32 v3, v3, v89, v91
	v_fmac_f32_e32 v3, v137, v90
	v_mul_f32_e32 v3, v74, v3
	v_cvt_pk_bf16_f32 v3, v3, v3
	v_lshl_add_u64 v[72:73], v[70:71], 0, v[66:67]
	global_store_short v[72:73], v3, off
	v_mul_f32_e32 v3, v85, v104
	v_fmac_f32_e32 v91, v3, v89
	v_fmac_f32_e32 v91, v133, v92
	v_mul_f32_e32 v3, v75, v91
	v_lshl_add_u64 v[66:67], v[64:65], 0, v[66:67]
	v_cvt_pk_bf16_f32 v3, v3, v3
	global_store_short v[66:67], v3, off
	global_load_dword v66, v190, s[50:51] offset:192
	s_nop 0
	global_load_dword v67, v190, s[52:53] offset:192
	s_waitcnt vmcnt(0)
	v_fma_f32 v2, v2, v66, v67
	v_fmac_f32_e32 v2, v132, v106
	v_mul_f32_e32 v2, v76, v2
	v_cvt_pk_bf16_f32 v72, v2, v2
	v_lshl_add_u64 v[2:3], v[68:69], 0, v[0:1]
	global_store_short v[2:3], v72, off
	v_mul_f32_e32 v2, v80, v102
	v_fma_f32 v2, v2, v66, v67
	v_fmac_f32_e32 v2, v134, v88
	v_mul_f32_e32 v2, v77, v2
	v_cvt_pk_bf16_f32 v68, v2, v2
	v_lshl_add_u64 v[2:3], v[86:87], 0, v[0:1]
	global_store_short v[2:3], v68, off
	v_mul_f32_e32 v2, v82, v105
	v_fma_f32 v2, v2, v66, v67
	v_fmac_f32_e32 v2, v135, v90
	v_mul_f32_e32 v2, v78, v2
	v_cvt_pk_bf16_f32 v68, v2, v2
	v_lshl_add_u64 v[2:3], v[70:71], 0, v[0:1]
	global_store_short v[2:3], v68, off
	v_mul_f32_e32 v2, v84, v104
	v_fmac_f32_e32 v67, v2, v66
	v_fmac_f32_e32 v67, v127, v92
	v_mul_f32_e32 v2, v79, v67
	v_cvt_pk_bf16_f32 v66, v2, v2
	v_lshl_add_u64 v[2:3], v[64:65], 0, v[0:1]
	global_store_short v[2:3], v66, off
	s_branch .LBB0_819
